# speedup vs baseline: 1.0329x; 1.0329x over previous
; __device__ __forceinline__ unsigned pk2(float lo, float hi) { f32x2 v = {lo, hi}; bf16x2_t b = __builtin_convertvector(v, bf16x2_t); return __builtin_bit_cast(unsigned, b); }
; __device__ __forceinline__ float silu_f(float z) { return z * __builtin_amdgcn_rcpf(1.0f + __expf(-z)); }
; __device__ __forceinline__ int launder_v(int x) { asm volatile("" : "+v"(x)); return x; }
; __device__ __forceinline__ int launder_s(int x) { asm volatile("" : "+s"(x)); return x; }
; __device__ __forceinline__ float swap_add(float v) { unsigned a = __builtin_bit_cast(unsigned, v), b = a; asm volatile("s_nop 1\n\tv_permlane32_swap_b32 %0, %1\n\ts_nop 1" : "+v"(a), "+v"(b)); return __builtin_bit_cast(float, a) + __builtin_bit_cast(float, b); }
; template <int MODE>
; __device__ __forceinline__ void attn_unit(LAS unsigned char* lds, const bf16_t* __restrict__ qkvz, bf16_t* __restrict__ A2, const int b, const int hd, const int qb, const AttnX& X, const int tid) {
;     ...
;     const float l_tot = swap_add(l_run);
;     const float inv = 1.0f / l_tot;
;     const int lane_e = launder_v(lane);
;     const size_t trow = (size_t)launder_s(b) * SEQ + launder_s(q0w) + (lane_e & 31);
;     if (MODE != 0) {
;         const int hh_e = lane_e >> 5;
;         u32x2 zz[NDT * 4];
; #pragma unroll
;         for (int d = 0; d < NDT; ++d)
; #pragma unroll
;             for (int i4 = 0; i4 < 4; ++i4) zz[d * 4 + i4] = *(const u32x2*)(qkvz + trow * LD + zcol + 32 * d + 8 * i4 + 4 * hh_e);
; #pragma unroll
;         for (int d = 0; d < NDT; ++d)
; #pragma unroll
;             for (int i4 = 0; i4 < 4; ++i4) { const int dd = 32 * d + 8 * i4 + 4 * hh_e; const u32x2 z2 = zz[d * 4 + i4];
;                 u32x2 w;
;                 w.x = pk2(O[d][4 * i4 + 0] * inv * silu_f(bflo(z2.x)), O[d][4 * i4 + 1] * inv * silu_f(bfhi(z2.x)));
;                 w.y = pk2(O[d][4 * i4 + 2] * inv * silu_f(bflo(z2.y)), O[d][4 * i4 + 3] * inv * silu_f(bfhi(z2.y)));
;                 *(u32x2*)(A2 + trow * DM + hd * C::DV + dd) = w; }
; __device__ __forceinline__ void phase_attn_fox(const Params& p, LAS unsigned char* lds) {
;     ...
;     for (int u = bx; u < 2048; u += G) { const int j = u & 255, r = u >> 8, bh = j & 63, gg = j >> 6;
;         const int qb = 31 - ((r & 1) ? 4 * r + 3 - gg : 4 * r + gg);
;         attn_unit<2>(lds, QKVZ, A2, bh >> 4, bh & 15, qb, X, tid); }
.LBB0_1003:
	s_or_b64 exec, exec, s[92:93]
	v_mov_b32_e32 v74, v190
	v_mov_b32_e32 v70, v161
	s_nop 1
	v_permlane32_swap_b32 v190, v74
	s_nop 1
	s_ashr_i32 s15, s14, 31
	s_lshl_b64 s[0:1], s[14:15], 13
	s_ashr_i32 s2, s13, 31
	s_add_u32 s0, s0, s13
	v_and_b32_e32 v0, 31, v70
	s_addc_u32 s1, s1, s2
	v_lshl_add_u64 v[66:67], s[0:1], 0, v[0:1]
	v_readlane_b32 s84, v255, 7
	v_ashrrev_i32_e32 v0, 3, v70
	v_lshlrev_b64 v[68:69], 14, v[66:67]
	v_readlane_b32 s85, v255, 8
	v_and_b32_e32 v70, -4, v0
	s_mov_b32 s13, s89
	v_lshl_add_u64 v[68:69], s[84:85], 0, v[68:69]
	v_ashrrev_i32_e32 v71, 31, v70
	v_lshl_add_u64 v[68:69], v[68:69], 0, s[12:13]
	v_lshlrev_b64 v[70:71], 1, v[70:71]
	v_lshl_add_u64 v[68:69], v[68:69], 0, v[70:71]
	s_movk_i32 s0, 0x3000
	v_add_co_u32_e32 v72, vcc, s0, v68
	s_mov_b64 s[0:1], 0x3000
	s_nop 0
	v_addc_co_u32_e32 v73, vcc, 0, v69, vcc
	global_load_dwordx2 v[90:91], v[72:73], off
	v_lshl_add_u64 v[68:69], v[68:69], 0, s[0:1]
	global_load_dwordx2 v[92:93], v[68:69], off offset:16
	global_load_dwordx2 v[94:95], v[68:69], off offset:32
	v_add_f32_e32 v0, v190, v74
	v_div_scale_f32 v100, s[0:1], v0, v0, 1.0
	v_rcp_f32_e32 v101, v100
	v_readlane_b32 s94, v255, 5
	v_lshlrev_b64 v[66:67], 12, v[66:67]
	v_readlane_b32 s95, v255, 6
	v_fma_f32 v72, -v100, v101, 1.0
	v_fmac_f32_e32 v101, v72, v101
	v_lshl_add_u64 v[66:67], s[94:95], 0, v[66:67]
	v_lshl_add_u64 v[66:67], v[66:67], 0, s[12:13]
	v_lshl_add_u64 v[66:67], v[66:67], 0, v[70:71]
	global_load_dwordx2 v[96:97], v[68:69], off offset:48
	global_load_dwordx2 v[98:99], v[68:69], off offset:64
	global_load_dwordx2 v[88:89], v[68:69], off offset:80
	global_load_dwordx2 v[86:87], v[68:69], off offset:96
	global_load_dwordx2 v[84:85], v[68:69], off offset:112
	global_load_dwordx2 v[82:83], v[68:69], off offset:128
	global_load_dwordx2 v[80:81], v[68:69], off offset:144
	global_load_dwordx2 v[78:79], v[68:69], off offset:160
	global_load_dwordx2 v[76:77], v[68:69], off offset:176
	global_load_dwordx2 v[74:75], v[68:69], off offset:192
	global_load_dwordx2 v[72:73], v[68:69], off offset:208
	global_load_dwordx2 v[70:71], v[68:69], off offset:224
	s_nop 0
	global_load_dwordx2 v[68:69], v[68:69], off offset:240
	v_div_scale_f32 v102, vcc, 1.0, v0, 1.0
	v_mul_f32_e32 v103, v102, v101
	v_fma_f32 v104, -v100, v103, v102
	v_fmac_f32_e32 v103, v104, v101
	v_fma_f32 v100, -v100, v103, v102
	v_div_fmas_f32 v100, v100, v101, v103
	v_div_fixup_f32 v0, v100, v0, 1.0
	v_pk_mul_f32 v[50:51], v[50:51], v[0:1] op_sel_hi:[1,0]
	v_pk_mul_f32 v[52:53], v[52:53], v[0:1] op_sel_hi:[1,0]
	v_pk_mul_f32 v[54:55], v[54:55], v[0:1] op_sel_hi:[1,0]
	v_pk_mul_f32 v[34:35], v[34:35], v[0:1] op_sel_hi:[1,0]
	v_pk_mul_f32 v[36:37], v[36:37], v[0:1] op_sel_hi:[1,0]
	v_pk_mul_f32 v[38:39], v[38:39], v[0:1] op_sel_hi:[1,0]
	v_pk_mul_f32 v[18:19], v[18:19], v[0:1] op_sel_hi:[1,0]
	v_pk_mul_f32 v[20:21], v[20:21], v[0:1] op_sel_hi:[1,0]
	v_pk_mul_f32 v[22:23], v[22:23], v[0:1] op_sel_hi:[1,0]
	v_pk_mul_f32 v[2:3], v[2:3], v[0:1] op_sel_hi:[1,0]
	v_pk_mul_f32 v[4:5], v[4:5], v[0:1] op_sel_hi:[1,0]
	v_pk_mul_f32 v[6:7], v[6:7], v[0:1] op_sel_hi:[1,0]
	v_readlane_b32 s0, v254, 47
	v_readlane_b32 s28, v255, 9
	v_readlane_b32 s92, v255, 4
	v_readlane_b32 s29, v255, 10
	s_waitcnt vmcnt(15)
	v_lshlrev_b32_e32 v100, 16, v90
	v_and_b32_e32 v101, 0xffff0000, v90
	v_lshlrev_b32_e32 v90, 16, v91
	v_and_b32_e32 v91, 0xffff0000, v91
	v_mul_f32_e32 v104, 0xbfb8aa3b, v100
	v_mul_f32_e32 v105, 0xbfb8aa3b, v101
	v_mul_f32_e32 v106, 0xbfb8aa3b, v90
	v_mul_f32_e32 v107, 0xbfb8aa3b, v91
	v_exp_f32_e32 v104, v104
	v_exp_f32_e32 v105, v105
	v_exp_f32_e32 v106, v106
	v_exp_f32_e32 v107, v107
	v_add_f32_e32 v104, 1.0, v104
	v_add_f32_e32 v105, 1.0, v105
	v_add_f32_e32 v106, 1.0, v106
	v_add_f32_e32 v107, 1.0, v107
	v_rcp_f32_e32 v104, v104
	v_rcp_f32_e32 v105, v105
	v_rcp_f32_e32 v106, v106
	v_rcp_f32_e32 v107, v107
	s_waitcnt vmcnt(14)
	v_lshlrev_b32_e32 v102, 16, v92
	v_and_b32_e32 v103, 0xffff0000, v92
	v_lshlrev_b32_e32 v92, 16, v93
	v_and_b32_e32 v93, 0xffff0000, v93
	v_mul_f32_e32 v108, 0xbfb8aa3b, v102
	v_mul_f32_e32 v109, 0xbfb8aa3b, v103
	v_pk_mul_f32 v[100:101], v[104:105], v[100:101]
	v_pk_mul_f32 v[90:91], v[106:107], v[90:91]
	v_mul_f32_e32 v110, 0xbfb8aa3b, v92
	v_mul_f32_e32 v111, 0xbfb8aa3b, v93
	v_exp_f32_e32 v108, v108
	v_exp_f32_e32 v109, v109
	v_pk_mul_f32 v[50:51], v[50:51], v[100:101]
	v_pk_mul_f32 v[52:53], v[52:53], v[90:91]
	v_exp_f32_e32 v110, v110
	v_cvt_pk_bf16_f32 v50, v50, v51
	v_cvt_pk_bf16_f32 v51, v52, v53
	v_exp_f32_e32 v53, v111
	v_add_f32_e32 v108, 1.0, v108
	v_add_f32_e32 v109, 1.0, v109
	v_rcp_f32_e32 v108, v108
	v_rcp_f32_e32 v109, v109
	v_add_f32_e32 v52, 1.0, v110
	v_add_f32_e32 v53, 1.0, v53
	v_rcp_f32_e32 v52, v52
	v_rcp_f32_e32 v53, v53
	global_store_dwordx2 v[66:67], v[50:51], off
	v_pk_mul_f32 v[50:51], v[108:109], v[102:103]
	v_pk_mul_f32 v[52:53], v[52:53], v[92:93]
	v_pk_mul_f32 v[50:51], v[54:55], v[50:51]
	v_pk_mul_f32 v[54:55], v[56:57], v[0:1] op_sel_hi:[1,0]
	v_cvt_pk_bf16_f32 v50, v50, v51
	v_pk_mul_f32 v[52:53], v[54:55], v[52:53]
	s_waitcnt vmcnt(14)
	v_lshlrev_b32_e32 v56, 16, v95
	v_cvt_pk_bf16_f32 v51, v52, v53
	global_store_dwordx2 v[66:67], v[50:51], off offset:16
	v_lshlrev_b32_e32 v50, 16, v94
	v_mul_f32_e32 v51, 0xbfb8aa3b, v50
	v_exp_f32_e32 v52, v51
	v_and_b32_e32 v51, 0xffff0000, v94
	v_mul_f32_e32 v53, 0xbfb8aa3b, v51
	v_exp_f32_e32 v53, v53
	v_and_b32_e32 v57, 0xffff0000, v95
	v_add_f32_e32 v52, 1.0, v52
	v_pk_mul_f32 v[54:55], v[58:59], v[0:1] op_sel_hi:[1,0]
	v_add_f32_e32 v53, 1.0, v53
	v_mul_f32_e32 v58, 0xbfb8aa3b, v56
	v_mul_f32_e32 v59, 0xbfb8aa3b, v57
	v_rcp_f32_e32 v52, v52
	v_rcp_f32_e32 v53, v53
	v_exp_f32_e32 v58, v58
	v_exp_f32_e32 v59, v59
	v_pk_mul_f32 v[50:51], v[52:53], v[50:51]
	v_add_f32_e32 v52, 1.0, v58
	v_add_f32_e32 v53, 1.0, v59
	v_rcp_f32_e32 v52, v52
	v_rcp_f32_e32 v53, v53
	v_pk_mul_f32 v[50:51], v[54:55], v[50:51]
	v_pk_mul_f32 v[54:55], v[60:61], v[0:1] op_sel_hi:[1,0]
	v_cvt_pk_bf16_f32 v50, v50, v51
	v_pk_mul_f32 v[52:53], v[52:53], v[56:57]
	s_waitcnt vmcnt(14)
; __device__ __forceinline__ unsigned pk2(float lo, float hi) { f32x2 v = {lo, hi}; bf16x2_t b = __builtin_convertvector(v, bf16x2_t); return __builtin_bit_cast(unsigned, b); }
; __device__ __forceinline__ float silu_f(float z) { return z * __builtin_amdgcn_rcpf(1.0f + __expf(-z)); }
; template <int MODE>
; __device__ __forceinline__ void attn_unit(LAS unsigned char* lds, const bf16_t* __restrict__ qkvz, bf16_t* __restrict__ A2, const int b, const int hd, const int qb, const AttnX& X, const int tid) {
;     ...
; #pragma unroll
;         for (int d = 0; d < NDT; ++d)
; #pragma unroll
;             for (int i4 = 0; i4 < 4; ++i4) { const int dd = 32 * d + 8 * i4 + 4 * hh_e; const u32x2 z2 = zz[d * 4 + i4];
;                 u32x2 w;
;                 w.x = pk2(O[d][4 * i4 + 0] * inv * silu_f(bflo(z2.x)), O[d][4 * i4 + 1] * inv * silu_f(bfhi(z2.x)));
;                 w.y = pk2(O[d][4 * i4 + 2] * inv * silu_f(bflo(z2.y)), O[d][4 * i4 + 3] * inv * silu_f(bfhi(z2.y)));
;                 *(u32x2*)(A2 + trow * DM + hd * C::DV + dd) = w; }
	v_lshlrev_b32_e32 v56, 16, v97
	v_pk_mul_f32 v[52:53], v[54:55], v[52:53]
	v_and_b32_e32 v57, 0xffff0000, v97
	v_cvt_pk_bf16_f32 v51, v52, v53
	global_store_dwordx2 v[66:67], v[50:51], off offset:32
	v_lshlrev_b32_e32 v50, 16, v96
	v_mul_f32_e32 v51, 0xbfb8aa3b, v50
	v_exp_f32_e32 v52, v51
	v_and_b32_e32 v51, 0xffff0000, v96
	v_mul_f32_e32 v53, 0xbfb8aa3b, v51
	v_exp_f32_e32 v53, v53
	v_add_f32_e32 v52, 1.0, v52
	v_mul_f32_e32 v58, 0xbfb8aa3b, v56
	v_mul_f32_e32 v59, 0xbfb8aa3b, v57
	v_add_f32_e32 v53, 1.0, v53
	v_rcp_f32_e32 v52, v52
	v_rcp_f32_e32 v53, v53
	v_exp_f32_e32 v58, v58
	v_exp_f32_e32 v59, v59
	v_pk_mul_f32 v[54:55], v[62:63], v[0:1] op_sel_hi:[1,0]
	v_pk_mul_f32 v[50:51], v[52:53], v[50:51]
	v_add_f32_e32 v52, 1.0, v58
	v_add_f32_e32 v53, 1.0, v59
	v_rcp_f32_e32 v52, v52
	v_rcp_f32_e32 v53, v53
	v_pk_mul_f32 v[50:51], v[54:55], v[50:51]
	v_pk_mul_f32 v[54:55], v[64:65], v[0:1] op_sel_hi:[1,0]
	v_cvt_pk_bf16_f32 v50, v50, v51
	v_pk_mul_f32 v[52:53], v[52:53], v[56:57]
	s_nop 0
	v_pk_mul_f32 v[52:53], v[54:55], v[52:53]
	s_waitcnt vmcnt(14)
	v_lshlrev_b32_e32 v54, 16, v99
	v_cvt_pk_bf16_f32 v51, v52, v53
	global_store_dwordx2 v[66:67], v[50:51], off offset:48
	v_lshlrev_b32_e32 v50, 16, v98
	v_mul_f32_e32 v51, 0xbfb8aa3b, v50
	v_exp_f32_e32 v52, v51
	v_and_b32_e32 v51, 0xffff0000, v98
	v_mul_f32_e32 v53, 0xbfb8aa3b, v51
	v_exp_f32_e32 v53, v53
	v_and_b32_e32 v55, 0xffff0000, v99
	v_add_f32_e32 v52, 1.0, v52
	v_mul_f32_e32 v56, 0xbfb8aa3b, v54
	v_add_f32_e32 v53, 1.0, v53
	v_mul_f32_e32 v57, 0xbfb8aa3b, v55
	v_rcp_f32_e32 v52, v52
	v_rcp_f32_e32 v53, v53
	v_exp_f32_e32 v56, v56
	v_exp_f32_e32 v57, v57
	v_pk_mul_f32 v[50:51], v[52:53], v[50:51]
	v_add_f32_e32 v52, 1.0, v56
	v_add_f32_e32 v53, 1.0, v57
	v_rcp_f32_e32 v52, v52
	v_rcp_f32_e32 v53, v53
	v_pk_mul_f32 v[34:35], v[34:35], v[50:51]
	v_pk_mul_f32 v[50:51], v[52:53], v[54:55]
	s_nop 0
	v_pk_mul_f32 v[36:37], v[36:37], v[50:51]
	v_cvt_pk_bf16_f32 v34, v34, v35
	v_cvt_pk_bf16_f32 v35, v36, v37
	global_store_dwordx2 v[66:67], v[34:35], off offset:64
	s_waitcnt vmcnt(15)
	v_lshlrev_b32_e32 v34, 16, v88
	v_mul_f32_e32 v35, 0xbfb8aa3b, v34
	v_exp_f32_e32 v36, v35
	v_and_b32_e32 v35, 0xffff0000, v88
	v_mul_f32_e32 v37, 0xbfb8aa3b, v35
	v_exp_f32_e32 v37, v37
	v_lshlrev_b32_e32 v50, 16, v89
	v_and_b32_e32 v51, 0xffff0000, v89
	v_add_f32_e32 v36, 1.0, v36
	v_add_f32_e32 v37, 1.0, v37
	v_mul_f32_e32 v52, 0xbfb8aa3b, v50
	v_mul_f32_e32 v53, 0xbfb8aa3b, v51
	v_rcp_f32_e32 v36, v36
	v_rcp_f32_e32 v37, v37
	v_exp_f32_e32 v52, v52
	v_exp_f32_e32 v53, v53
	v_pk_mul_f32 v[34:35], v[36:37], v[34:35]
	v_add_f32_e32 v36, 1.0, v52
	v_add_f32_e32 v37, 1.0, v53
	v_rcp_f32_e32 v36, v36
	v_rcp_f32_e32 v37, v37
	v_pk_mul_f32 v[34:35], v[38:39], v[34:35]
	v_pk_mul_f32 v[38:39], v[40:41], v[0:1] op_sel_hi:[1,0]
	v_cvt_pk_bf16_f32 v34, v34, v35
	v_pk_mul_f32 v[36:37], v[36:37], v[50:51]
	s_waitcnt vmcnt(14)
	v_lshlrev_b32_e32 v40, 16, v87
	v_pk_mul_f32 v[36:37], v[38:39], v[36:37]
	v_and_b32_e32 v41, 0xffff0000, v87
	v_cvt_pk_bf16_f32 v35, v36, v37
	global_store_dwordx2 v[66:67], v[34:35], off offset:80
	v_lshlrev_b32_e32 v34, 16, v86
	v_mul_f32_e32 v35, 0xbfb8aa3b, v34
	v_exp_f32_e32 v36, v35
	v_and_b32_e32 v35, 0xffff0000, v86
	v_mul_f32_e32 v37, 0xbfb8aa3b, v35
	v_exp_f32_e32 v37, v37
	v_add_f32_e32 v36, 1.0, v36
	v_pk_mul_f32 v[38:39], v[42:43], v[0:1] op_sel_hi:[1,0]
	v_mul_f32_e32 v42, 0xbfb8aa3b, v40
	v_add_f32_e32 v37, 1.0, v37
	v_mul_f32_e32 v43, 0xbfb8aa3b, v41
	v_rcp_f32_e32 v36, v36
	v_rcp_f32_e32 v37, v37
	v_exp_f32_e32 v42, v42
	v_exp_f32_e32 v43, v43
	v_pk_mul_f32 v[34:35], v[36:37], v[34:35]
	v_add_f32_e32 v36, 1.0, v42
	v_add_f32_e32 v37, 1.0, v43
	v_rcp_f32_e32 v36, v36
	v_rcp_f32_e32 v37, v37
	v_pk_mul_f32 v[34:35], v[38:39], v[34:35]
	v_pk_mul_f32 v[38:39], v[44:45], v[0:1] op_sel_hi:[1,0]
	v_cvt_pk_bf16_f32 v34, v34, v35
	v_pk_mul_f32 v[36:37], v[36:37], v[40:41]
	s_waitcnt vmcnt(14)
	v_lshlrev_b32_e32 v40, 16, v85
	v_pk_mul_f32 v[36:37], v[38:39], v[36:37]
	v_and_b32_e32 v41, 0xffff0000, v85
	v_cvt_pk_bf16_f32 v35, v36, v37
	global_store_dwordx2 v[66:67], v[34:35], off offset:96
	v_lshlrev_b32_e32 v34, 16, v84
	v_mul_f32_e32 v35, 0xbfb8aa3b, v34
	v_exp_f32_e32 v36, v35
	v_and_b32_e32 v35, 0xffff0000, v84
	v_mul_f32_e32 v37, 0xbfb8aa3b, v35
	v_exp_f32_e32 v37, v37
	v_add_f32_e32 v36, 1.0, v36
	v_mul_f32_e32 v42, 0xbfb8aa3b, v40
	v_mul_f32_e32 v43, 0xbfb8aa3b, v41
	v_add_f32_e32 v37, 1.0, v37
	v_rcp_f32_e32 v36, v36
	v_rcp_f32_e32 v37, v37
	v_exp_f32_e32 v42, v42
	v_exp_f32_e32 v43, v43
	v_pk_mul_f32 v[38:39], v[46:47], v[0:1] op_sel_hi:[1,0]
	v_pk_mul_f32 v[34:35], v[36:37], v[34:35]
	v_add_f32_e32 v36, 1.0, v42
	v_add_f32_e32 v37, 1.0, v43
	v_rcp_f32_e32 v36, v36
	v_rcp_f32_e32 v37, v37
	v_pk_mul_f32 v[34:35], v[38:39], v[34:35]
	v_pk_mul_f32 v[38:39], v[48:49], v[0:1] op_sel_hi:[1,0]
	v_cvt_pk_bf16_f32 v34, v34, v35
	v_pk_mul_f32 v[36:37], v[36:37], v[40:41]
	s_nop 0
	v_pk_mul_f32 v[36:37], v[38:39], v[36:37]
	s_waitcnt vmcnt(14)
	v_lshlrev_b32_e32 v38, 16, v83
	v_cvt_pk_bf16_f32 v35, v36, v37
	global_store_dwordx2 v[66:67], v[34:35], off offset:112
	v_lshlrev_b32_e32 v34, 16, v82
	v_mul_f32_e32 v35, 0xbfb8aa3b, v34
	v_exp_f32_e32 v36, v35
	v_and_b32_e32 v35, 0xffff0000, v82
	v_mul_f32_e32 v37, 0xbfb8aa3b, v35
	v_exp_f32_e32 v37, v37
	v_and_b32_e32 v39, 0xffff0000, v83
	v_add_f32_e32 v36, 1.0, v36
	v_mul_f32_e32 v40, 0xbfb8aa3b, v38
	v_add_f32_e32 v37, 1.0, v37
	v_mul_f32_e32 v41, 0xbfb8aa3b, v39
	v_rcp_f32_e32 v36, v36
	v_rcp_f32_e32 v37, v37
	v_exp_f32_e32 v40, v40
	v_exp_f32_e32 v41, v41
	v_pk_mul_f32 v[34:35], v[36:37], v[34:35]
	v_add_f32_e32 v36, 1.0, v40
	v_add_f32_e32 v37, 1.0, v41
	v_rcp_f32_e32 v36, v36
	v_rcp_f32_e32 v37, v37
	v_pk_mul_f32 v[18:19], v[18:19], v[34:35]
	v_pk_mul_f32 v[34:35], v[36:37], v[38:39]
	s_nop 0
	v_pk_mul_f32 v[20:21], v[20:21], v[34:35]
	v_cvt_pk_bf16_f32 v18, v18, v19
	v_cvt_pk_bf16_f32 v19, v20, v21
	global_store_dwordx2 v[66:67], v[18:19], off offset:128
	s_waitcnt vmcnt(15)
; __device__ __forceinline__ unsigned pk2(float lo, float hi) { f32x2 v = {lo, hi}; bf16x2_t b = __builtin_convertvector(v, bf16x2_t); return __builtin_bit_cast(unsigned, b); }
; __device__ __forceinline__ float silu_f(float z) { return z * __builtin_amdgcn_rcpf(1.0f + __expf(-z)); }
; template <int MODE>
; __device__ __forceinline__ void attn_unit(LAS unsigned char* lds, const bf16_t* __restrict__ qkvz, bf16_t* __restrict__ A2, const int b, const int hd, const int qb, const AttnX& X, const int tid) {
;     ...
; #pragma unroll
;         for (int d = 0; d < NDT; ++d)
; #pragma unroll
;             for (int i4 = 0; i4 < 4; ++i4) { const int dd = 32 * d + 8 * i4 + 4 * hh_e; const u32x2 z2 = zz[d * 4 + i4];
;                 u32x2 w;
;                 w.x = pk2(O[d][4 * i4 + 0] * inv * silu_f(bflo(z2.x)), O[d][4 * i4 + 1] * inv * silu_f(bfhi(z2.x)));
;                 w.y = pk2(O[d][4 * i4 + 2] * inv * silu_f(bflo(z2.y)), O[d][4 * i4 + 3] * inv * silu_f(bfhi(z2.y)));
;                 *(u32x2*)(A2 + trow * DM + hd * C::DV + dd) = w; }
;     ...
;     __syncthreads();
	v_lshlrev_b32_e32 v18, 16, v80
	v_mul_f32_e32 v19, 0xbfb8aa3b, v18
	v_exp_f32_e32 v20, v19
	v_and_b32_e32 v19, 0xffff0000, v80
	v_mul_f32_e32 v21, 0xbfb8aa3b, v19
	v_exp_f32_e32 v21, v21
	v_lshlrev_b32_e32 v34, 16, v81
	v_and_b32_e32 v35, 0xffff0000, v81
	v_add_f32_e32 v20, 1.0, v20
	v_add_f32_e32 v21, 1.0, v21
	v_mul_f32_e32 v36, 0xbfb8aa3b, v34
	v_mul_f32_e32 v37, 0xbfb8aa3b, v35
	v_rcp_f32_e32 v20, v20
	v_rcp_f32_e32 v21, v21
	v_exp_f32_e32 v36, v36
	v_exp_f32_e32 v37, v37
	v_pk_mul_f32 v[18:19], v[20:21], v[18:19]
	v_add_f32_e32 v20, 1.0, v36
	v_add_f32_e32 v21, 1.0, v37
	v_rcp_f32_e32 v20, v20
	v_rcp_f32_e32 v21, v21
	v_pk_mul_f32 v[18:19], v[22:23], v[18:19]
	v_pk_mul_f32 v[22:23], v[24:25], v[0:1] op_sel_hi:[1,0]
	v_cvt_pk_bf16_f32 v18, v18, v19
	v_pk_mul_f32 v[20:21], v[20:21], v[34:35]
	s_waitcnt vmcnt(14)
	v_lshlrev_b32_e32 v24, 16, v79
	v_pk_mul_f32 v[20:21], v[22:23], v[20:21]
	v_and_b32_e32 v25, 0xffff0000, v79
	v_cvt_pk_bf16_f32 v19, v20, v21
	global_store_dwordx2 v[66:67], v[18:19], off offset:144
	v_lshlrev_b32_e32 v18, 16, v78
	v_mul_f32_e32 v19, 0xbfb8aa3b, v18
	v_exp_f32_e32 v20, v19
	v_and_b32_e32 v19, 0xffff0000, v78
	v_mul_f32_e32 v21, 0xbfb8aa3b, v19
	v_exp_f32_e32 v21, v21
	v_add_f32_e32 v20, 1.0, v20
	v_pk_mul_f32 v[22:23], v[26:27], v[0:1] op_sel_hi:[1,0]
	v_mul_f32_e32 v26, 0xbfb8aa3b, v24
	v_add_f32_e32 v21, 1.0, v21
	v_mul_f32_e32 v27, 0xbfb8aa3b, v25
	v_rcp_f32_e32 v20, v20
	v_rcp_f32_e32 v21, v21
	v_exp_f32_e32 v26, v26
	v_exp_f32_e32 v27, v27
	v_pk_mul_f32 v[18:19], v[20:21], v[18:19]
	v_add_f32_e32 v20, 1.0, v26
	v_add_f32_e32 v21, 1.0, v27
	v_rcp_f32_e32 v20, v20
	v_rcp_f32_e32 v21, v21
	v_pk_mul_f32 v[18:19], v[22:23], v[18:19]
	v_pk_mul_f32 v[22:23], v[28:29], v[0:1] op_sel_hi:[1,0]
	v_cvt_pk_bf16_f32 v18, v18, v19
	v_pk_mul_f32 v[20:21], v[20:21], v[24:25]
	s_waitcnt vmcnt(14)
	v_lshlrev_b32_e32 v24, 16, v77
	v_pk_mul_f32 v[20:21], v[22:23], v[20:21]
	v_and_b32_e32 v25, 0xffff0000, v77
	v_cvt_pk_bf16_f32 v19, v20, v21
	global_store_dwordx2 v[66:67], v[18:19], off offset:160
	v_lshlrev_b32_e32 v18, 16, v76
	v_mul_f32_e32 v19, 0xbfb8aa3b, v18
	v_exp_f32_e32 v20, v19
	v_and_b32_e32 v19, 0xffff0000, v76
	v_mul_f32_e32 v21, 0xbfb8aa3b, v19
	v_exp_f32_e32 v21, v21
	v_add_f32_e32 v20, 1.0, v20
	v_mul_f32_e32 v26, 0xbfb8aa3b, v24
	v_mul_f32_e32 v27, 0xbfb8aa3b, v25
	v_add_f32_e32 v21, 1.0, v21
	v_rcp_f32_e32 v20, v20
	v_rcp_f32_e32 v21, v21
	v_exp_f32_e32 v26, v26
	v_exp_f32_e32 v27, v27
	v_pk_mul_f32 v[22:23], v[30:31], v[0:1] op_sel_hi:[1,0]
	v_pk_mul_f32 v[18:19], v[20:21], v[18:19]
	v_add_f32_e32 v20, 1.0, v26
	v_add_f32_e32 v21, 1.0, v27
	v_rcp_f32_e32 v20, v20
	v_rcp_f32_e32 v21, v21
	v_pk_mul_f32 v[18:19], v[22:23], v[18:19]
	v_pk_mul_f32 v[22:23], v[32:33], v[0:1] op_sel_hi:[1,0]
	v_cvt_pk_bf16_f32 v18, v18, v19
	v_pk_mul_f32 v[20:21], v[20:21], v[24:25]
	s_nop 0
	v_pk_mul_f32 v[20:21], v[22:23], v[20:21]
	s_waitcnt vmcnt(14)
	v_lshlrev_b32_e32 v22, 16, v75
	v_cvt_pk_bf16_f32 v19, v20, v21
	global_store_dwordx2 v[66:67], v[18:19], off offset:176
	v_lshlrev_b32_e32 v18, 16, v74
	v_mul_f32_e32 v19, 0xbfb8aa3b, v18
	v_exp_f32_e32 v20, v19
	v_and_b32_e32 v19, 0xffff0000, v74
	v_mul_f32_e32 v21, 0xbfb8aa3b, v19
	v_exp_f32_e32 v21, v21
	v_and_b32_e32 v23, 0xffff0000, v75
	v_add_f32_e32 v20, 1.0, v20
	v_mul_f32_e32 v24, 0xbfb8aa3b, v22
	v_add_f32_e32 v21, 1.0, v21
	v_mul_f32_e32 v25, 0xbfb8aa3b, v23
	v_rcp_f32_e32 v20, v20
	v_rcp_f32_e32 v21, v21
	v_exp_f32_e32 v24, v24
	v_exp_f32_e32 v25, v25
	v_pk_mul_f32 v[18:19], v[20:21], v[18:19]
	v_add_f32_e32 v20, 1.0, v24
	v_add_f32_e32 v21, 1.0, v25
	v_rcp_f32_e32 v20, v20
	v_rcp_f32_e32 v21, v21
	v_pk_mul_f32 v[2:3], v[2:3], v[18:19]
	v_pk_mul_f32 v[18:19], v[20:21], v[22:23]
	s_nop 0
	v_pk_mul_f32 v[4:5], v[4:5], v[18:19]
	v_cvt_pk_bf16_f32 v2, v2, v3
	v_cvt_pk_bf16_f32 v3, v4, v5
	global_store_dwordx2 v[66:67], v[2:3], off offset:192
	s_waitcnt vmcnt(15)
	v_lshlrev_b32_e32 v2, 16, v72
	v_mul_f32_e32 v3, 0xbfb8aa3b, v2
	v_exp_f32_e32 v4, v3
	v_and_b32_e32 v3, 0xffff0000, v72
	v_mul_f32_e32 v5, 0xbfb8aa3b, v3
	v_exp_f32_e32 v5, v5
	v_lshlrev_b32_e32 v18, 16, v73
	v_and_b32_e32 v19, 0xffff0000, v73
	v_add_f32_e32 v4, 1.0, v4
	v_add_f32_e32 v5, 1.0, v5
	v_mul_f32_e32 v20, 0xbfb8aa3b, v18
	v_mul_f32_e32 v21, 0xbfb8aa3b, v19
	v_rcp_f32_e32 v4, v4
	v_rcp_f32_e32 v5, v5
	v_exp_f32_e32 v20, v20
	v_exp_f32_e32 v21, v21
	v_pk_mul_f32 v[2:3], v[4:5], v[2:3]
	v_add_f32_e32 v4, 1.0, v20
	v_add_f32_e32 v5, 1.0, v21
	v_rcp_f32_e32 v4, v4
	v_rcp_f32_e32 v5, v5
	v_pk_mul_f32 v[2:3], v[6:7], v[2:3]
	v_pk_mul_f32 v[6:7], v[8:9], v[0:1] op_sel_hi:[1,0]
	v_cvt_pk_bf16_f32 v2, v2, v3
	v_pk_mul_f32 v[4:5], v[4:5], v[18:19]
	s_waitcnt vmcnt(14)
	v_lshlrev_b32_e32 v8, 16, v71
	v_pk_mul_f32 v[4:5], v[6:7], v[4:5]
	v_and_b32_e32 v9, 0xffff0000, v71
	v_cvt_pk_bf16_f32 v3, v4, v5
	global_store_dwordx2 v[66:67], v[2:3], off offset:208
	v_lshlrev_b32_e32 v2, 16, v70
	v_mul_f32_e32 v3, 0xbfb8aa3b, v2
	v_exp_f32_e32 v4, v3
	v_and_b32_e32 v3, 0xffff0000, v70
	v_mul_f32_e32 v5, 0xbfb8aa3b, v3
	v_exp_f32_e32 v5, v5
	v_add_f32_e32 v4, 1.0, v4
	v_pk_mul_f32 v[6:7], v[10:11], v[0:1] op_sel_hi:[1,0]
	v_mul_f32_e32 v10, 0xbfb8aa3b, v8
	v_add_f32_e32 v5, 1.0, v5
	v_mul_f32_e32 v11, 0xbfb8aa3b, v9
	v_rcp_f32_e32 v4, v4
	v_rcp_f32_e32 v5, v5
	v_exp_f32_e32 v10, v10
	v_exp_f32_e32 v11, v11
	v_pk_mul_f32 v[2:3], v[4:5], v[2:3]
	v_add_f32_e32 v4, 1.0, v10
	v_add_f32_e32 v5, 1.0, v11
	v_rcp_f32_e32 v4, v4
	v_rcp_f32_e32 v5, v5
	v_pk_mul_f32 v[2:3], v[6:7], v[2:3]
	v_pk_mul_f32 v[6:7], v[12:13], v[0:1] op_sel_hi:[1,0]
	v_cvt_pk_bf16_f32 v2, v2, v3
	v_pk_mul_f32 v[4:5], v[4:5], v[8:9]
	s_waitcnt vmcnt(14)
	v_lshlrev_b32_e32 v8, 16, v69
	v_pk_mul_f32 v[4:5], v[6:7], v[4:5]
	v_and_b32_e32 v9, 0xffff0000, v69
	v_cvt_pk_bf16_f32 v3, v4, v5
	global_store_dwordx2 v[66:67], v[2:3], off offset:224
	v_lshlrev_b32_e32 v2, 16, v68
	v_mul_f32_e32 v3, 0xbfb8aa3b, v2
	v_exp_f32_e32 v4, v3
	v_and_b32_e32 v3, 0xffff0000, v68
	v_mul_f32_e32 v5, 0xbfb8aa3b, v3
	v_exp_f32_e32 v5, v5
	v_add_f32_e32 v4, 1.0, v4
	v_mul_f32_e32 v10, 0xbfb8aa3b, v8
	v_mul_f32_e32 v11, 0xbfb8aa3b, v9
	v_add_f32_e32 v5, 1.0, v5
	v_rcp_f32_e32 v4, v4
	v_rcp_f32_e32 v5, v5
	v_exp_f32_e32 v10, v10
	v_exp_f32_e32 v11, v11
	v_pk_mul_f32 v[6:7], v[14:15], v[0:1] op_sel_hi:[1,0]
	v_pk_mul_f32 v[2:3], v[4:5], v[2:3]
	v_add_f32_e32 v4, 1.0, v10
	v_add_f32_e32 v5, 1.0, v11
	v_rcp_f32_e32 v4, v4
	v_rcp_f32_e32 v5, v5
	v_pk_mul_f32 v[2:3], v[6:7], v[2:3]
	v_pk_mul_f32 v[6:7], v[16:17], v[0:1] op_sel_hi:[1,0]
	v_cvt_pk_bf16_f32 v2, v2, v3
	v_pk_mul_f32 v[4:5], v[4:5], v[8:9]
	s_nop 0
	v_pk_mul_f32 v[4:5], v[6:7], v[4:5]
	s_nop 0
	v_cvt_pk_bf16_f32 v3, v4, v5
	global_store_dwordx2 v[66:67], v[2:3], off offset:240
	s_waitcnt lgkmcnt(0)
	s_barrier
; __device__ __forceinline__ void phase_attn_fox(const Params& p, LAS unsigned char* lds) {
;     ...
;     for (int u = bx; u < 2048; u += G) { const int j = u & 255, r = u >> 8, bh = j & 63, gg = j >> 6;
;         const int qb = 31 - ((r & 1) ? 4 * r + 3 - gg : 4 * r + gg);
;         attn_unit<2>(lds, QKVZ, A2, bh >> 4, bh & 15, qb, X, tid); }
	v_readlane_b32 s98, v254, 51
	v_readlane_b32 s99, v254, 52
	v_cmp_eq_u32_e32 vcc, 0, v212
	s_and_saveexec_b64 s[100:101], vcc
	s_cbranch_execz .Lfox_nofetch
	v_mov_b32_e32 v2, 0x93a0080
	v_mov_b32_e32 v3, 1
	s_nop 1
	global_atomic_add v2, v2, v3, s[98:99] sc0
	s_waitcnt vmcnt(0)
	v_mov_b32_e32 v3, 0x23ff8
	ds_write_b32 v3, v2
.Lfox_nofetch:
	s_or_b64 exec, exec, s[100:101]
	s_waitcnt lgkmcnt(0)
	s_barrier
	v_mov_b32_e32 v3, 0x23ff8
	ds_read_b32 v2, v3
	v_readlane_b32 s100, v254, 47
	s_waitcnt lgkmcnt(0)
	v_readfirstlane_b32 s87, v2
	s_nop 1
	s_add_i32 s87, s87, s100
	s_cmpk_lt_i32 s87, 0x800
	s_cbranch_scc0 .LBB0_1057

; #define LAS __attribute__((address_space(3)))
; __global__ void __launch_bounds__(NTHREADS, 2) mega_fwd(Params p) {
;     extern __shared__ __attribute__((aligned(16))) unsigned char lds_raw[];
;     LAS unsigned char* lds = (LAS unsigned char*)lds_raw;
	.amdhsa_kernel _Z8mega_fwd6Params
		.amdhsa_group_segment_fixed_size 0
		.amdhsa_private_segment_fixed_size 0
		.amdhsa_kernarg_size 456
		.amdhsa_user_sgpr_count 2
		.amdhsa_user_sgpr_dispatch_ptr 0
		.amdhsa_user_sgpr_queue_ptr 0
		.amdhsa_user_sgpr_kernarg_segment_ptr 1
		.amdhsa_user_sgpr_dispatch_id 0
		.amdhsa_user_sgpr_kernarg_preload_length 0
		.amdhsa_user_sgpr_kernarg_preload_offset 0
		.amdhsa_user_sgpr_private_segment_size 0
		.amdhsa_uses_dynamic_stack 0
		.amdhsa_enable_private_segment 0
		.amdhsa_system_sgpr_workgroup_id_x 1
		.amdhsa_system_sgpr_workgroup_id_y 0
		.amdhsa_system_sgpr_workgroup_id_z 0
		.amdhsa_system_sgpr_workgroup_info 0
		.amdhsa_system_vgpr_workitem_id 2
		.amdhsa_next_free_vgpr 256
		.amdhsa_next_free_sgpr 102
		.amdhsa_accum_offset 256
		.amdhsa_reserve_vcc 1
		.amdhsa_float_round_mode_32 0
		.amdhsa_float_round_mode_16_64 0
		.amdhsa_float_denorm_mode_32 3
		.amdhsa_float_denorm_mode_16_64 3
		.amdhsa_dx10_clamp 1
		.amdhsa_ieee_mode 1
		.amdhsa_fp16_overflow 0
		.amdhsa_tg_split 0
		.amdhsa_exception_fp_ieee_invalid_op 0
		.amdhsa_exception_fp_denorm_src 0
		.amdhsa_exception_fp_ieee_div_zero 0
		.amdhsa_exception_fp_ieee_overflow 0
		.amdhsa_exception_fp_ieee_underflow 0
		.amdhsa_exception_fp_ieee_inexact 0
		.amdhsa_exception_int_div_zero 0
	.end_amdhsa_kernel

; #define LAS __attribute__((address_space(3)))
; __global__ void __launch_bounds__(NTHREADS, 2) mega_fwd(Params p) {
;     extern __shared__ __attribute__((aligned(16))) unsigned char lds_raw[];
;     LAS unsigned char* lds = (LAS unsigned char*)lds_raw;
amdhsa.kernels:
  - .agpr_count:     0
    .args:
      - .offset:         0
        .size:           200
        .value_kind:     by_value
      - .offset:         200
        .size:           4
        .value_kind:     hidden_block_count_x
      - .offset:         204
        .size:           4
        .value_kind:     hidden_block_count_y
      - .offset:         208
        .size:           4
        .value_kind:     hidden_block_count_z
      - .offset:         212
        .size:           2
        .value_kind:     hidden_group_size_x
      - .offset:         214
        .size:           2
        .value_kind:     hidden_group_size_y
      - .offset:         216
        .size:           2
        .value_kind:     hidden_group_size_z
      - .offset:         218
        .size:           2
        .value_kind:     hidden_remainder_x
      - .offset:         220
        .size:           2
        .value_kind:     hidden_remainder_y
      - .offset:         222
        .size:           2
        .value_kind:     hidden_remainder_z
      - .offset:         240
        .size:           8
        .value_kind:     hidden_global_offset_x
      - .offset:         248
        .size:           8
        .value_kind:     hidden_global_offset_y
      - .offset:         256
        .size:           8
        .value_kind:     hidden_global_offset_z
      - .offset:         264
        .size:           2
        .value_kind:     hidden_grid_dims
      - .offset:         288
        .size:           8
        .value_kind:     hidden_multigrid_sync_arg
      - .offset:         320
        .size:           4
        .value_kind:     hidden_dynamic_lds_size
    .group_segment_fixed_size: 0
    .kernarg_segment_align: 8
    .kernarg_segment_size: 456
    .language:       OpenCL C
    .language_version:
      - 2
      - 0
    .max_flat_workgroup_size: 512
    .name:           _Z8mega_fwd6Params
    .private_segment_fixed_size: 0
    .sgpr_count:     108
    .sgpr_spill_count: 77
    .symbol:         _Z8mega_fwd6Params.kd
    .uniform_work_group_size: 1
    .uses_dynamic_stack: false
    .vgpr_count:     256
    .vgpr_spill_count: 0
    .wavefront_size: 64
